# comb13 + grid barrier: XCD leader issues its invalidate right after its L2 writeback (overlaps the top-level arrive/spin) instead of after the spin
# baseline (speedup 1.0000x reference)
; __device__ __forceinline__ unsigned xb_ld(unsigned* p)              { return __hip_atomic_load(p, __ATOMIC_RELAXED, __HIP_MEMORY_SCOPE_AGENT); }
; __device__ __forceinline__ unsigned xb_add(unsigned* p, unsigned v) { return __hip_atomic_fetch_add(p, v, __ATOMIC_RELAXED, __HIP_MEMORY_SCOPE_AGENT); }
; #define XB_SPIN(cond, bar) do { unsigned _sp = 0; while (cond) { __builtin_amdgcn_s_sleep(1); \
;     if ((++_sp & 255u) == 0u) { if (xb_ld(&(bar)[XB_TMO])) break; if (_sp > XB_SPIN_CAP) { atomicAdd(&(bar)[XB_TMO], 1u); break; } } } } while (0)
; __device__ __forceinline__ void xcd_barrier(const XcdBarrier& b) {
;     ...
;         if (old + 1u == (gen + 1u) * nloc) {
;             __builtin_amdgcn_fence(__ATOMIC_RELEASE, "agent");
;             asm volatile("s_waitcnt vmcnt(0)" ::: "memory");
;             const unsigned og = xb_add(&bar[XB_TOP], 1u);
;             const unsigned tg = og / nx;
;             if (og + 1u == (tg + 1u) * nx) xb_add(&bar[XB_TOPGEN], 1u);
;             else XB_SPIN(xb_ld(&bar[XB_TOPGEN]) == tg, bar);
;             __builtin_amdgcn_fence(__ATOMIC_ACQUIRE, "agent");
;             xb_add(&bar[XB_XGEN(b.x)], 1u);
;             asm volatile("s_waitcnt vmcnt(0)" ::: "memory");
.LBB0_117:
	s_andn2_saveexec_b64 s[6:7], s[6:7]
	s_cbranch_execz .LBB0_135
	s_mov_b64 s[6:7], exec
	buffer_wbl2 sc1
	s_waitcnt lgkmcnt(0)
	s_waitcnt vmcnt(0)
	buffer_inv sc1
	v_mbcnt_lo_u32_b32 v2, s6, 0
	v_mbcnt_hi_u32_b32 v2, s7, v2
	v_cmp_eq_u32_e32 vcc, 0, v2
	s_and_saveexec_b64 s[8:9], vcc
	s_cbranch_execz .LBB0_120
	s_bcnt1_i32_b64 s6, s[6:7]
	v_mov_b32_e32 v3, 0x3f52f000
	v_mov_b32_e32 v4, s6
	global_atomic_add v3, v3, v4, s[30:31] offset:1024 sc0

; __device__ __forceinline__ unsigned xb_add(unsigned* p, unsigned v) { return __hip_atomic_fetch_add(p, v, __ATOMIC_RELAXED, __HIP_MEMORY_SCOPE_AGENT); }
; __device__ __forceinline__ void xcd_barrier(const XcdBarrier& b) {
;     ...
;             __builtin_amdgcn_fence(__ATOMIC_ACQUIRE, "agent");
;             xb_add(&bar[XB_XGEN(b.x)], 1u);
;             asm volatile("s_waitcnt vmcnt(0)" ::: "memory");
.LBB0_134:
	s_or_b64 exec, exec, s[6:7]
	v_mov_b32_e32 v1, 0x2000
	v_mov_b32_e32 v2, 1
	s_waitcnt vmcnt(0)
	global_atomic_add v1, v2, s[4:5] offset:1024
	s_waitcnt vmcnt(0)

; __device__ __forceinline__ unsigned xb_ld(unsigned* p)              { return __hip_atomic_load(p, __ATOMIC_RELAXED, __HIP_MEMORY_SCOPE_AGENT); }
; __device__ __forceinline__ unsigned xb_add(unsigned* p, unsigned v) { return __hip_atomic_fetch_add(p, v, __ATOMIC_RELAXED, __HIP_MEMORY_SCOPE_AGENT); }
; #define XB_SPIN(cond, bar) do { unsigned _sp = 0; while (cond) { __builtin_amdgcn_s_sleep(1); \
;     if ((++_sp & 255u) == 0u) { if (xb_ld(&(bar)[XB_TMO])) break; if (_sp > XB_SPIN_CAP) { atomicAdd(&(bar)[XB_TMO], 1u); break; } } } } while (0)
; __device__ __forceinline__ void xcd_barrier(const XcdBarrier& b) {
;     ...
;         if (old + 1u == (gen + 1u) * nloc) {
;             __builtin_amdgcn_fence(__ATOMIC_RELEASE, "agent");
;             asm volatile("s_waitcnt vmcnt(0)" ::: "memory");
;             const unsigned og = xb_add(&bar[XB_TOP], 1u);
;             const unsigned tg = og / nx;
;             if (og + 1u == (tg + 1u) * nx) xb_add(&bar[XB_TOPGEN], 1u);
;             else XB_SPIN(xb_ld(&bar[XB_TOPGEN]) == tg, bar);
;             __builtin_amdgcn_fence(__ATOMIC_ACQUIRE, "agent");
;             xb_add(&bar[XB_XGEN(b.x)], 1u);
;             asm volatile("s_waitcnt vmcnt(0)" ::: "memory");
.LBB0_189:
	s_andn2_saveexec_b64 s[8:9], s[8:9]
	s_cbranch_execz .LBB0_207
	s_mov_b64 s[8:9], exec
	buffer_wbl2 sc1
	s_waitcnt lgkmcnt(0)
	s_waitcnt vmcnt(0)
	buffer_inv sc1
	v_mbcnt_lo_u32_b32 v3, s8, 0
	v_mbcnt_hi_u32_b32 v3, s9, v3
	v_cmp_eq_u32_e32 vcc, 0, v3
	s_and_saveexec_b64 s[10:11], vcc
	s_cbranch_execz .LBB0_192
	s_bcnt1_i32_b64 s8, s[8:9]
	v_mov_b32_e32 v4, 0x3f52f000
	v_mov_b32_e32 v5, s8
	global_atomic_add v4, v4, v5, s[30:31] offset:1024 sc0

; __device__ __forceinline__ unsigned xb_add(unsigned* p, unsigned v) { return __hip_atomic_fetch_add(p, v, __ATOMIC_RELAXED, __HIP_MEMORY_SCOPE_AGENT); }
; __device__ __forceinline__ void xcd_barrier(const XcdBarrier& b) {
;     ...
;             __builtin_amdgcn_fence(__ATOMIC_ACQUIRE, "agent");
;             xb_add(&bar[XB_XGEN(b.x)], 1u);
;             asm volatile("s_waitcnt vmcnt(0)" ::: "memory");
.LBB0_206:
	s_or_b64 exec, exec, s[8:9]
	v_mov_b32_e32 v2, 0x2000
	v_mov_b32_e32 v3, 1
	s_waitcnt vmcnt(0)
	global_atomic_add v2, v3, s[4:5] offset:1024
	s_waitcnt vmcnt(0)

; __device__ __forceinline__ unsigned xb_ld(unsigned* p)              { return __hip_atomic_load(p, __ATOMIC_RELAXED, __HIP_MEMORY_SCOPE_AGENT); }
; __device__ __forceinline__ unsigned xb_add(unsigned* p, unsigned v) { return __hip_atomic_fetch_add(p, v, __ATOMIC_RELAXED, __HIP_MEMORY_SCOPE_AGENT); }
; #define XB_SPIN(cond, bar) do { unsigned _sp = 0; while (cond) { __builtin_amdgcn_s_sleep(1); \
;     if ((++_sp & 255u) == 0u) { if (xb_ld(&(bar)[XB_TMO])) break; if (_sp > XB_SPIN_CAP) { atomicAdd(&(bar)[XB_TMO], 1u); break; } } } } while (0)
; __device__ __forceinline__ void xcd_barrier(const XcdBarrier& b) {
;     ...
;         if (old + 1u == (gen + 1u) * nloc) {
;             __builtin_amdgcn_fence(__ATOMIC_RELEASE, "agent");
;             asm volatile("s_waitcnt vmcnt(0)" ::: "memory");
;             const unsigned og = xb_add(&bar[XB_TOP], 1u);
;             const unsigned tg = og / nx;
;             if (og + 1u == (tg + 1u) * nx) xb_add(&bar[XB_TOPGEN], 1u);
;             else XB_SPIN(xb_ld(&bar[XB_TOPGEN]) == tg, bar);
;             __builtin_amdgcn_fence(__ATOMIC_ACQUIRE, "agent");
;             xb_add(&bar[XB_XGEN(b.x)], 1u);
;             asm volatile("s_waitcnt vmcnt(0)" ::: "memory");
.LBB0_322:
	s_andn2_saveexec_b64 s[6:7], s[6:7]
	s_cbranch_execz .LBB0_340
	s_mov_b64 s[6:7], exec
	buffer_wbl2 sc1
	s_waitcnt lgkmcnt(0)
	s_waitcnt vmcnt(0)
	buffer_inv sc1
	v_mbcnt_lo_u32_b32 v3, s6, 0
	v_mbcnt_hi_u32_b32 v3, s7, v3
	v_cmp_eq_u32_e32 vcc, 0, v3
	s_and_saveexec_b64 s[10:11], vcc
	s_cbranch_execz .LBB0_325
	s_bcnt1_i32_b64 s6, s[6:7]
	v_mov_b32_e32 v4, 0x3f52f000
	v_mov_b32_e32 v5, s6
	global_atomic_add v4, v4, v5, s[30:31] offset:1024 sc0

; __device__ __forceinline__ unsigned xb_add(unsigned* p, unsigned v) { return __hip_atomic_fetch_add(p, v, __ATOMIC_RELAXED, __HIP_MEMORY_SCOPE_AGENT); }
; __device__ __forceinline__ void xcd_barrier(const XcdBarrier& b) {
;     ...
;             __builtin_amdgcn_fence(__ATOMIC_ACQUIRE, "agent");
;             xb_add(&bar[XB_XGEN(b.x)], 1u);
;             asm volatile("s_waitcnt vmcnt(0)" ::: "memory");
.LBB0_339:
	s_or_b64 exec, exec, s[6:7]
	v_mov_b32_e32 v2, 0x2000
	v_mov_b32_e32 v3, 1
	s_waitcnt vmcnt(0)
	global_atomic_add v2, v3, s[4:5] offset:1024
	s_waitcnt vmcnt(0)

; __device__ __forceinline__ unsigned xb_ld(unsigned* p)              { return __hip_atomic_load(p, __ATOMIC_RELAXED, __HIP_MEMORY_SCOPE_AGENT); }
; __device__ __forceinline__ unsigned xb_add(unsigned* p, unsigned v) { return __hip_atomic_fetch_add(p, v, __ATOMIC_RELAXED, __HIP_MEMORY_SCOPE_AGENT); }
; #define XB_SPIN(cond, bar) do { unsigned _sp = 0; while (cond) { __builtin_amdgcn_s_sleep(1); \
;     if ((++_sp & 255u) == 0u) { if (xb_ld(&(bar)[XB_TMO])) break; if (_sp > XB_SPIN_CAP) { atomicAdd(&(bar)[XB_TMO], 1u); break; } } } } while (0)
; __device__ __forceinline__ void xcd_barrier(const XcdBarrier& b) {
;     ...
;         if (old + 1u == (gen + 1u) * nloc) {
;             __builtin_amdgcn_fence(__ATOMIC_RELEASE, "agent");
;             asm volatile("s_waitcnt vmcnt(0)" ::: "memory");
;             const unsigned og = xb_add(&bar[XB_TOP], 1u);
;             const unsigned tg = og / nx;
;             if (og + 1u == (tg + 1u) * nx) xb_add(&bar[XB_TOPGEN], 1u);
;             else XB_SPIN(xb_ld(&bar[XB_TOPGEN]) == tg, bar);
;             __builtin_amdgcn_fence(__ATOMIC_ACQUIRE, "agent");
;             xb_add(&bar[XB_XGEN(b.x)], 1u);
;             asm volatile("s_waitcnt vmcnt(0)" ::: "memory");
.LBB0_720:
	s_andn2_saveexec_b64 s[6:7], s[6:7]
	s_cbranch_execz .LBB0_738
	s_mov_b64 s[6:7], exec
	buffer_wbl2 sc1
	s_waitcnt lgkmcnt(0)
	s_waitcnt vmcnt(0)
	buffer_inv sc1
	v_mbcnt_lo_u32_b32 v3, s6, 0
	v_mbcnt_hi_u32_b32 v3, s7, v3
	v_cmp_eq_u32_e32 vcc, 0, v3
	s_and_saveexec_b64 s[8:9], vcc
	s_cbranch_execz .LBB0_723
	s_bcnt1_i32_b64 s6, s[6:7]
	v_mov_b32_e32 v4, 0x3f52f000
	v_mov_b32_e32 v5, s6
	global_atomic_add v4, v4, v5, s[30:31] offset:1024 sc0

; __device__ __forceinline__ unsigned xb_ld(unsigned* p)              { return __hip_atomic_load(p, __ATOMIC_RELAXED, __HIP_MEMORY_SCOPE_AGENT); }
; __device__ __forceinline__ unsigned xb_add(unsigned* p, unsigned v) { return __hip_atomic_fetch_add(p, v, __ATOMIC_RELAXED, __HIP_MEMORY_SCOPE_AGENT); }
; #define XB_SPIN(cond, bar) do { unsigned _sp = 0; while (cond) { __builtin_amdgcn_s_sleep(1); \
;     if ((++_sp & 255u) == 0u) { if (xb_ld(&(bar)[XB_TMO])) break; if (_sp > XB_SPIN_CAP) { atomicAdd(&(bar)[XB_TMO], 1u); break; } } } } while (0)
; __device__ __forceinline__ void xcd_barrier(const XcdBarrier& b) {
;     ...
;         if (old + 1u == (gen + 1u) * nloc) {
;             __builtin_amdgcn_fence(__ATOMIC_RELEASE, "agent");
;             asm volatile("s_waitcnt vmcnt(0)" ::: "memory");
;             const unsigned og = xb_add(&bar[XB_TOP], 1u);
;             const unsigned tg = og / nx;
;             if (og + 1u == (tg + 1u) * nx) xb_add(&bar[XB_TOPGEN], 1u);
;             else XB_SPIN(xb_ld(&bar[XB_TOPGEN]) == tg, bar);
;             __builtin_amdgcn_fence(__ATOMIC_ACQUIRE, "agent");
;             xb_add(&bar[XB_XGEN(b.x)], 1u);
;             asm volatile("s_waitcnt vmcnt(0)" ::: "memory");
.LBB0_2276:
	s_andn2_saveexec_b64 s[4:5], s[4:5]
	s_cbranch_execz .LBB0_2294
	s_mov_b64 s[4:5], exec
	buffer_wbl2 sc1
	s_waitcnt lgkmcnt(0)
	s_waitcnt vmcnt(0)
	buffer_inv sc1
	v_mbcnt_lo_u32_b32 v3, s4, 0
	v_mbcnt_hi_u32_b32 v3, s5, v3
	v_cmp_eq_u32_e32 vcc, 0, v3
	s_and_saveexec_b64 s[8:9], vcc
	s_cbranch_execz .LBB0_2279
	s_bcnt1_i32_b64 s4, s[4:5]
	v_mov_b32_e32 v4, 0x3f52f000
	v_mov_b32_e32 v5, s4
	global_atomic_add v4, v4, v5, s[30:31] offset:1024 sc0

; __device__ __forceinline__ unsigned xb_add(unsigned* p, unsigned v) { return __hip_atomic_fetch_add(p, v, __ATOMIC_RELAXED, __HIP_MEMORY_SCOPE_AGENT); }
; __device__ __forceinline__ void xcd_barrier(const XcdBarrier& b) {
;     ...
;             __builtin_amdgcn_fence(__ATOMIC_ACQUIRE, "agent");
;             xb_add(&bar[XB_XGEN(b.x)], 1u);
;             asm volatile("s_waitcnt vmcnt(0)" ::: "memory");
.LBB0_2293:
	s_or_b64 exec, exec, s[4:5]
	v_mov_b32_e32 v2, 0x2000
	v_mov_b32_e32 v3, 1
	s_waitcnt vmcnt(0)
	global_atomic_add v2, v3, s[2:3] offset:1024
	s_waitcnt vmcnt(0)
